# gate unit order: the two workgroups of a pn pair read the same A tile at the same time (fixed B tile per workgroup)
# speedup vs baseline: 1.0241x; 1.0202x over previous
;     __device__ bool next(int i, Unit& u) const {
;         if (sticky) { u.pn = c % nN; u.pm = c / nN + i * (G / nN); return u.pm < nM; }
;         const long L = (long)i * G + c; if (L >= nwg) return false;
;         int wgid = (int)L; { const int q = nwg / NXCD, r = nwg % NXCD, xcd = wgid % NXCD, off = wgid / NXCD; wgid = (xcd < r ? xcd * (q + 1) : r * (q + 1) + (xcd - r) * q) + off; }
;         const int nig = WGM * nN, gid = wgid / nig, fm = gid * WGM, gsz = (nM - fm) < WGM ? (nM - fm) : WGM;
;         u.pm = fm + ((wgid % nig) % gsz); u.pn = (wgid % nig) / gsz; return true;
; template <class Epi>
; __device__ __forceinline__ void gemm_phase(LAS unsigned char* lds, const Gemm g, const StaticOrder& S_in, const Epi& E, int sw) {
;     ...
;     Unit cur, nxt; int ui = 0;
;     if (!S.next(0, cur)) return;
.LBB0_419:
	s_or_b64 exec, exec, s[8:9]
	s_mov_b64 s[8:9], s[92:93]
	s_waitcnt lgkmcnt(0)
	s_barrier
	s_load_dwordx2 s[12:13], s[8:9], 0xa8
	s_mov_b64 s[8:9], s[92:93]
	s_mov_b64 s[10:11], s[92:93]
	s_load_dwordx2 s[8:9], s[8:9], 0xa8
	s_load_dwordx2 s[10:11], s[10:11], 0xa8
	s_mov_b32 s16, s75
	s_mov_b32 s17, s81
	s_lshl_b32 s80, s36, 4
	v_mbcnt_lo_u32_b32 v0, -1, s17
	v_mbcnt_hi_u32_b32 v0, -1, v0
	v_lshl_add_u32 v26, s16, 6, v0
	s_cmp_lt_i32 s20, s80
	s_cselect_b64 s[16:17], -1, 0
	s_cmp_ge_i32 s20, s80
	v_readfirstlane_b32 s37, v26
	s_cbranch_scc1 .LBB0_421
	s_ashr_i32 s18, s20, 31
	s_lshr_b32 s18, s18, 29
	s_add_i32 s18, s20, s18
	s_ashr_i32 s19, s18, 3
	s_and_b32 s18, s18, -8
	s_sub_i32 s18, s20, s18
	v_mov_b32_e32 v0, s18
	v_alignbit_b32 v0, s36, v0, 31
	s_nop 0
	v_readfirstlane_b32 s21, v0
	s_mul_i32 s18, s21, s18
	s_add_i32 s18, s18, s19
	s_ashr_i32 s19, s18, 31
	s_lshr_b32 s19, s19, 25
	s_add_i32 s19, s18, s19
	s_ashr_i32 s21, s19, 7
	s_lshl_b32 s21, s21, 3
	s_sub_i32 s22, s36, s21
	s_min_i32 s23, s22, 8
	s_abs_i32 s22, s23
	v_cvt_f32_u32_e32 v0, s22
	s_sub_i32 s25, 0, s22
	s_and_b32 s19, s19, 0xffffff80
	s_sub_i32 s18, s18, s19
	v_rcp_iflag_f32_e32 v0, v0
	s_abs_i32 s19, s18
	s_xor_b32 s24, s18, s23
	s_ashr_i32 s24, s24, 31
	v_mul_f32_e32 v0, 0x4f7ffffe, v0
	v_cvt_u32_f32_e32 v0, v0
	s_nop 0
	v_readfirstlane_b32 s26, v0
	s_mul_i32 s25, s25, s26
	s_mul_hi_u32 s25, s26, s25
	s_add_i32 s26, s26, s25
	s_mul_hi_u32 s25, s19, s26
	s_mul_i32 s26, s25, s22
	s_sub_i32 s19, s19, s26
	s_add_i32 s27, s25, 1
	s_sub_i32 s26, s19, s22
	s_cmp_ge_u32 s19, s22
	s_cselect_b32 s25, s27, s25
	s_cselect_b32 s19, s26, s19
	s_add_i32 s26, s25, 1
	s_cmp_ge_u32 s19, s22
	s_cselect_b32 s19, s26, s25
	s_xor_b32 s19, s19, s24
	s_sub_i32 s22, s19, s24
	s_mul_i32 s19, s22, s23
	s_sub_i32 s18, s18, s19
	s_add_i32 s24, s18, s21
	s_cmp_lg_u32 s15, 32
	s_cbranch_scc1 .Lgate_ord0_keep
	s_cmp_lg_u32 s36, 16
	s_cbranch_scc1 .Lgate_ord0_keep
	s_lshr_b32 s24, s20, 4
	s_and_b32 s22, s20, 15

;     __device__ bool next(int i, Unit& u) const {
;         if (sticky) { u.pn = c % nN; u.pm = c / nN + i * (G / nN); return u.pm < nM; }
;         const long L = (long)i * G + c; if (L >= nwg) return false;
;         int wgid = (int)L; { const int q = nwg / NXCD, r = nwg % NXCD, xcd = wgid % NXCD, off = wgid / NXCD; wgid = (xcd < r ? xcd * (q + 1) : r * (q + 1) + (xcd - r) * q) + off; }
;         const int nig = WGM * nN, gid = wgid / nig, fm = gid * WGM, gsz = (nM - fm) < WGM ? (nM - fm) : WGM;
;         u.pm = fm + ((wgid % nig) % gsz); u.pn = (wgid % nig) / gsz; return true;
; template <class Epi>
; __device__ __forceinline__ void gemm_phase(LAS unsigned char* lds, const Gemm g, const StaticOrder& S_in, const Epi& E, int sw) {
;     ...
;         const bool has_next = S.next(ui + 1, nxt);
;         const char* nA = has_next ? PG8_ABASE(nxt) : cA; const char* nB = has_next ? PG8_BBASE(nxt) : cB;
.LBB0_426:
	v_mov_b64_e32 v[18:19], s[80:81]
	v_cmp_ge_i64_e32 vcc, s[0:1], v[18:19]
	v_cmp_lt_i64_e64 s[4:5], s[0:1], v[18:19]
	s_cbranch_vccnz .LBB0_428
	s_ashr_i32 s12, s0, 31
	s_lshr_b32 s12, s12, 29
	s_add_i32 s12, s0, s12
	s_ashr_i32 s13, s12, 3
	s_and_b32 s12, s12, -8
	s_sub_i32 s12, s0, s12
	v_mov_b32_e32 v18, s12
	v_alignbit_b32 v18, s36, v18, 31
	s_nop 0
	v_readfirstlane_b32 s16, v18
	s_mul_i32 s12, s16, s12
	s_add_i32 s12, s12, s13
	s_ashr_i32 s13, s12, 31
	s_lshr_b32 s13, s13, 25
	s_add_i32 s13, s12, s13
	s_ashr_i32 s16, s13, 7
	s_lshl_b32 s16, s16, 3
	s_sub_i32 s17, s36, s16
	s_min_i32 s17, s17, 8
	s_abs_i32 s18, s17
	v_cvt_f32_u32_e32 v18, s18
	s_sub_i32 s20, 0, s18
	s_and_b32 s13, s13, 0xffffff80
	s_sub_i32 s13, s12, s13
	v_rcp_iflag_f32_e32 v18, v18
	s_abs_i32 s12, s13
	s_xor_b32 s19, s13, s17
	s_ashr_i32 s19, s19, 31
	v_mul_f32_e32 v18, 0x4f7ffffe, v18
	v_cvt_u32_f32_e32 v18, v18
	s_nop 0
	v_readfirstlane_b32 s21, v18
	s_mul_i32 s20, s20, s21
	s_mul_hi_u32 s20, s21, s20
	s_add_i32 s21, s21, s20
	s_mul_hi_u32 s20, s12, s21
	s_mul_i32 s21, s20, s18
	s_sub_i32 s12, s12, s21
	s_add_i32 s30, s20, 1
	s_sub_i32 s21, s12, s18
	s_cmp_ge_u32 s12, s18
	s_cselect_b32 s20, s30, s20
	s_cselect_b32 s12, s21, s12
	s_add_i32 s21, s20, 1
	s_cmp_ge_u32 s12, s18
	s_cselect_b32 s12, s21, s20
	s_xor_b32 s12, s12, s19
	s_sub_i32 s12, s12, s19
	s_mul_i32 s17, s12, s17
	s_sub_i32 s13, s13, s17
	s_add_i32 s16, s13, s16
	s_cmp_lg_u32 s15, 32
	s_cbranch_scc1 .Lgate_ord_keep
	s_cmp_lg_u32 s36, 16
	s_cbranch_scc1 .Lgate_ord_keep
	s_lshr_b32 s16, s0, 5
	s_lshl_b32 s16, s16, 1
	s_bfe_u32 s13, s0, 0x10004
	s_or_b32 s16, s16, s13
	s_and_b32 s12, s0, 15
